# noS6 plus LRU: waves 4-7 sleep 1024 cycles after each 4-chunk group barrier (SIMD partner stagger)
# baseline (speedup 1.0000x reference)
.LBB0_341:
	s_waitcnt lgkmcnt(0)
	s_barrier
	s_cmpk_lt_u32 s97, 0x100
	s_cbranch_scc1 .Lmy_lru_nd_LBB0_341
	s_sleep 16
.Lmy_lru_nd_LBB0_341:
	s_cmp_lt_u32 s16, 28
	s_cselect_b64 s[52:53], -1, 0
	s_cmp_gt_u32 s16, 27
	s_cbranch_scc0 .LBB0_336
	s_branch .LBB0_337

.Lmy_lru_nd_LBB0_355:
	s_cmp_lt_u32 s14, 28
	s_cselect_b64 s[46:47], -1, 0
	s_cmp_gt_u32 s14, 27
	s_cbranch_scc0 .LBB0_350
	s_branch .LBB0_351

.Lmy_lru_nd_LBB0_435:
	s_cmp_lt_u32 s34, 60
	s_cselect_b64 s[48:49], -1, 0
	s_cmp_gt_u32 s34, 59
	s_cbranch_scc0 .LBB0_430
	s_branch .LBB0_431

.LBB0_440:
	s_and_b32 s2, s48, 3
	s_cmp_lg_u32 s2, 0
	s_cbranch_scc1 .LBB0_442
	s_waitcnt lgkmcnt(0)
	s_barrier
	s_cmpk_lt_u32 s97, 0x100
	s_cbranch_scc1 .Lmy_lru_nd_LBB0_441
	s_sleep 16
.Lmy_lru_nd_LBB0_441:
.LBB0_442:
	s_cmp_lt_u32 s48, 60
	s_cselect_b64 s[46:47], -1, 0
	s_cmp_gt_u32 s48, 59
	v_lshl_add_u64 v[200:201], v[182:183], 0, s[44:45]
	s_cbranch_scc1 .LBB0_444
	v_add_co_u32_e32 v0, vcc, 0x3c100000, v200
	s_nop 1
	v_addc_co_u32_e32 v1, vcc, 0, v201, vcc
	global_load_dwordx4 v[160:163], v[0:1], off
